# attention SB store_o: 8-lane row-sum by three v_add_f32_dpp (xor1, xor2, half-mirror) instead of three serialized ds_bpermute + lgkmcnt(0) hops
# baseline (speedup 1.0000x reference)
.LBB0_435:
	v_cvt_pk_bf16_f32 v16, v16, v161
	s_nop 2
	ds_write_b16 v160, v16
	v_cvt_pk_bf16_f32 v16, v17, v161
	ds_write_b16 v160, v16 offset:128
	v_cvt_pk_bf16_f32 v16, v18, v161
	ds_write_b16 v160, v16 offset:256
	v_cvt_pk_bf16_f32 v16, v19, v161
	ds_write_b16 v160, v16 offset:384
	v_cvt_pk_bf16_f32 v16, v20, v161
	ds_write_b16 v160, v16 offset:1024
	v_cvt_pk_bf16_f32 v16, v21, v161
	ds_write_b16 v160, v16 offset:1152
	v_cvt_pk_bf16_f32 v16, v22, v161
	ds_write_b16 v160, v16 offset:1280
	v_cvt_pk_bf16_f32 v16, v23, v161
	ds_write_b16 v160, v16 offset:1408
	v_cvt_pk_bf16_f32 v16, v24, v161
	ds_write_b16 v160, v16 offset:2048
	v_cvt_pk_bf16_f32 v16, v25, v161
	ds_write_b16 v160, v16 offset:2176
	v_cvt_pk_bf16_f32 v16, v26, v161
	ds_write_b16 v160, v16 offset:2304
	v_cvt_pk_bf16_f32 v16, v27, v161
	ds_write_b16 v160, v16 offset:2432
	v_cvt_pk_bf16_f32 v16, v28, v161
	ds_write_b16 v160, v16 offset:3072
	v_cvt_pk_bf16_f32 v16, v29, v161
	ds_write_b16 v160, v16 offset:3200
	v_cvt_pk_bf16_f32 v16, v30, v161
	ds_write_b16 v160, v16 offset:3328
	v_cvt_pk_bf16_f32 v16, v31, v161
	ds_write_b16 v160, v16 offset:3456
	v_cvt_pk_bf16_f32 v0, v0, v161
	ds_write_b16 v160, v0 offset:64
	v_cvt_pk_bf16_f32 v0, v1, v161
	ds_write_b16 v160, v0 offset:192
	v_cvt_pk_bf16_f32 v0, v2, v161
	ds_write_b16 v160, v0 offset:320
	v_cvt_pk_bf16_f32 v0, v3, v161
	ds_write_b16 v160, v0 offset:448
	v_cvt_pk_bf16_f32 v0, v4, v161
	ds_write_b16 v160, v0 offset:1088
	v_cvt_pk_bf16_f32 v0, v5, v161
	ds_write_b16 v160, v0 offset:1216
	v_cvt_pk_bf16_f32 v0, v6, v161
	ds_write_b16 v160, v0 offset:1344
	v_cvt_pk_bf16_f32 v0, v7, v161
	ds_write_b16 v160, v0 offset:1472
	v_cvt_pk_bf16_f32 v0, v8, v161
	ds_write_b16 v160, v0 offset:2112
	v_cvt_pk_bf16_f32 v0, v9, v161
	ds_write_b16 v160, v0 offset:2240
	v_cvt_pk_bf16_f32 v0, v10, v161
	ds_write_b16 v160, v0 offset:2368
	v_cvt_pk_bf16_f32 v0, v11, v161
	s_lshl_b32 s0, s92, 5
	ds_write_b16 v160, v0 offset:2496
	v_cvt_pk_bf16_f32 v0, v12, v161
	s_or_b32 s0, s0, s88
	ds_write_b16 v160, v0 offset:3136
	v_cvt_pk_bf16_f32 v0, v13, v161
	s_ashr_i32 s1, s0, 31
	ds_write_b16 v160, v0 offset:3264
	v_cvt_pk_bf16_f32 v0, v14, v161
	v_and_b32_e32 v2, 64, v188
	s_lshl_b64 vcc, s[0:1], 12
	ds_write_b16 v160, v0 offset:3392
	v_cvt_pk_bf16_f32 v0, v15, v161
	v_xor_b32_e32 v3, 1, v188
	v_add_u32_e32 v4, 64, v2
	ds_write_b16 v160, v0 offset:3520
	v_lshl_add_u64 v[0:1], v[150:151], 0, vcc
	v_cmp_lt_i32_e32 vcc, v3, v4
	s_waitcnt lgkmcnt(0)
	v_lshl_add_u64 v[8:9], v[0:1], 0, v[134:135]
	s_lshl_b64 s[0:1], s[0:1], 3
	v_cndmask_b32_e32 v3, v188, v3, vcc
	v_lshlrev_b32_e32 v190, 2, v3
	v_xor_b32_e32 v3, 2, v188
	v_cmp_lt_i32_e32 vcc, v3, v4
	s_add_u32 s0, s54, s0
	s_addc_u32 s1, s55, s1
	v_cndmask_b32_e32 v3, v188, v3, vcc
	v_lshlrev_b32_e32 v191, 2, v3
	v_xor_b32_e32 v3, 4, v188
	v_cmp_lt_i32_e32 vcc, v3, v4
	ds_read_b128 v[4:7], v172
	s_waitcnt lgkmcnt(0)
	global_store_dwordx4 v[8:9], v[4:7], off offset:2048
	v_cndmask_b32_e32 v3, v188, v3, vcc
	v_lshlrev_b32_e32 v192, 2, v3
	v_lshlrev_b32_e32 v3, 16, v4
	v_and_b32_e32 v4, 0xffff0000, v4
	v_mul_f32_e32 v4, v4, v4
	v_fmac_f32_e32 v4, v3, v3
	v_lshlrev_b32_e32 v3, 16, v5
	v_and_b32_e32 v5, 0xffff0000, v5
	v_mul_f32_e32 v5, v5, v5
	v_fmac_f32_e32 v5, v3, v3
	v_add_f32_e32 v3, v4, v5
	v_and_b32_e32 v5, 0xffff0000, v6
	v_lshlrev_b32_e32 v4, 16, v6
	v_mul_f32_e32 v5, v5, v5
	v_fmac_f32_e32 v5, v4, v4
	v_add_f32_e32 v3, v5, v3
	v_and_b32_e32 v5, 0xffff0000, v7
	v_lshlrev_b32_e32 v4, 16, v7
	v_mul_f32_e32 v5, v5, v5
	v_fmac_f32_e32 v5, v4, v4
	v_add_f32_e32 v3, v5, v3
	s_nop 1
	v_add_f32_dpp v3, v3, v3 quad_perm:[1,0,3,2] row_mask:0xf bank_mask:0xf
	s_nop 1
	v_add_f32_dpp v3, v3, v3 quad_perm:[2,3,0,1] row_mask:0xf bank_mask:0xf
	s_nop 1
	v_add_f32_dpp v3, v3, v3 row_half_mirror row_mask:0xf bank_mask:0xf
	s_and_saveexec_b64 vcc, s[6:7]
	s_cbranch_execz .LBB0_437
	v_lshl_add_u64 v[6:7], v[136:137], 2, s[0:1]
	s_waitcnt lgkmcnt(0)
	global_atomic_add_f32 v[6:7], v3, off offset:4
.LBB0_437:
	s_or_b64 exec, exec, vcc
	s_waitcnt lgkmcnt(0)
	ds_read_b128 v[4:7], v173
	v_lshl_add_u64 v[8:9], v[0:1], 0, v[138:139]
	s_waitcnt lgkmcnt(0)
	global_store_dwordx4 v[8:9], v[4:7], off offset:2048
	v_lshlrev_b32_e32 v3, 16, v4
	s_nop 0
	v_and_b32_e32 v4, 0xffff0000, v4
	v_mul_f32_e32 v4, v4, v4
	v_fmac_f32_e32 v4, v3, v3
	v_lshlrev_b32_e32 v3, 16, v5
	v_and_b32_e32 v5, 0xffff0000, v5
	v_mul_f32_e32 v5, v5, v5
	v_fmac_f32_e32 v5, v3, v3
	v_add_f32_e32 v3, v4, v5
	v_and_b32_e32 v5, 0xffff0000, v6
	v_lshlrev_b32_e32 v4, 16, v6
	v_mul_f32_e32 v5, v5, v5
	v_fmac_f32_e32 v5, v4, v4
	v_add_f32_e32 v3, v5, v3
	v_and_b32_e32 v5, 0xffff0000, v7
	v_lshlrev_b32_e32 v4, 16, v7
	v_mul_f32_e32 v5, v5, v5
	v_fmac_f32_e32 v5, v4, v4
	v_add_f32_e32 v3, v5, v3
	s_nop 1
	v_add_f32_dpp v3, v3, v3 quad_perm:[1,0,3,2] row_mask:0xf bank_mask:0xf
	s_nop 1
	v_add_f32_dpp v3, v3, v3 quad_perm:[2,3,0,1] row_mask:0xf bank_mask:0xf
	s_nop 1
	v_add_f32_dpp v3, v3, v3 row_half_mirror row_mask:0xf bank_mask:0xf
	s_and_saveexec_b64 vcc, s[6:7]
	s_cbranch_execz .LBB0_439
	v_lshl_add_u64 v[6:7], v[140:141], 2, s[0:1]
	s_waitcnt lgkmcnt(0)
	global_atomic_add_f32 v[6:7], v3, off offset:4
.LBB0_439:
	s_or_b64 exec, exec, vcc
	s_waitcnt lgkmcnt(0)
	ds_read_b128 v[4:7], v174
	v_lshl_add_u64 v[8:9], v[0:1], 0, v[142:143]
	s_waitcnt lgkmcnt(0)
	global_store_dwordx4 v[8:9], v[4:7], off offset:2048
	v_lshlrev_b32_e32 v3, 16, v4
	s_nop 0
	v_and_b32_e32 v4, 0xffff0000, v4
	v_mul_f32_e32 v4, v4, v4
	v_fmac_f32_e32 v4, v3, v3
	v_lshlrev_b32_e32 v3, 16, v5
	v_and_b32_e32 v5, 0xffff0000, v5
	v_mul_f32_e32 v5, v5, v5
	v_fmac_f32_e32 v5, v3, v3
	v_add_f32_e32 v3, v4, v5
	v_and_b32_e32 v5, 0xffff0000, v6
	v_lshlrev_b32_e32 v4, 16, v6
	v_mul_f32_e32 v5, v5, v5
	v_fmac_f32_e32 v5, v4, v4
	v_add_f32_e32 v3, v5, v3
	v_and_b32_e32 v5, 0xffff0000, v7
	v_lshlrev_b32_e32 v4, 16, v7
	v_mul_f32_e32 v5, v5, v5
	v_fmac_f32_e32 v5, v4, v4
	v_add_f32_e32 v3, v5, v3
	s_nop 1
	v_add_f32_dpp v3, v3, v3 quad_perm:[1,0,3,2] row_mask:0xf bank_mask:0xf
	s_nop 1
	v_add_f32_dpp v3, v3, v3 quad_perm:[2,3,0,1] row_mask:0xf bank_mask:0xf
	s_nop 1
	v_add_f32_dpp v3, v3, v3 row_half_mirror row_mask:0xf bank_mask:0xf
	s_and_saveexec_b64 vcc, s[6:7]
	s_cbranch_execz .LBB0_441
	v_lshl_add_u64 v[6:7], v[144:145], 2, s[0:1]
	s_waitcnt lgkmcnt(0)
	global_atomic_add_f32 v[6:7], v3, off offset:4
.LBB0_441:
	s_or_b64 exec, exec, vcc
	s_waitcnt lgkmcnt(0)
	ds_read_b128 v[4:7], v175
	v_lshl_add_u64 v[0:1], v[0:1], 0, v[146:147]
	s_waitcnt lgkmcnt(0)
	global_store_dwordx4 v[0:1], v[4:7], off offset:2048
	v_and_b32_e32 v1, 0xffff0000, v4
	v_lshlrev_b32_e32 v0, 16, v4
	v_mul_f32_e32 v1, v1, v1
	v_and_b32_e32 v3, 0xffff0000, v5
	v_fmac_f32_e32 v1, v0, v0
	v_lshlrev_b32_e32 v0, 16, v5
	v_mul_f32_e32 v3, v3, v3
	v_fmac_f32_e32 v3, v0, v0
	v_add_f32_e32 v0, v1, v3
	v_and_b32_e32 v3, 0xffff0000, v6
	v_lshlrev_b32_e32 v1, 16, v6
	v_mul_f32_e32 v3, v3, v3
	v_fmac_f32_e32 v3, v1, v1
	v_add_f32_e32 v0, v3, v0
	v_and_b32_e32 v3, 0xffff0000, v7
	v_lshlrev_b32_e32 v1, 16, v7
	v_mul_f32_e32 v3, v3, v3
	v_fmac_f32_e32 v3, v1, v1
	v_add_f32_e32 v0, v3, v0
	s_nop 1
	v_add_f32_dpp v0, v0, v0 quad_perm:[1,0,3,2] row_mask:0xf bank_mask:0xf
	s_nop 1
	v_add_f32_dpp v0, v0, v0 quad_perm:[2,3,0,1] row_mask:0xf bank_mask:0xf
	s_nop 1
	v_add_f32_dpp v0, v0, v0 row_half_mirror row_mask:0xf bank_mask:0xf
	s_and_saveexec_b64 vcc, s[6:7]
	s_cbranch_execz .LBB0_423
	v_lshl_add_u64 v[4:5], v[148:149], 2, s[0:1]
	s_waitcnt lgkmcnt(0)
	global_atomic_add_f32 v[4:5], v0, off offset:4
	s_branch .LBB0_423
